# diff-attn: two key tiles per barrier with 4-slot K/V rings (DMA for the next pair issued at pair start)
# speedup vs baseline: 1.0344x; 1.0020x over previous
; template <int MODE>
; __device__ __forceinline__ void attn_phase(LAS unsigned char* lds, const bf16* Qp, const bf16* Kp, const bf16* KPEp, const bf16* Vtp, bf16* CAT, float lam, int vcu, int G) {
;     ...
;         int tid_ = threadIdx.x; asm volatile("" : "+v"(tid_)); const int tid = tid_, lane = tid & 63, wave = __builtin_amdgcn_readfirstlane(tid >> 6), r = lane & 31, hh = lane >> 5;
;         int b, h, q0, wq, map, bh;
;         if (MODE == 0) { const int qb = unit & 31; bh = unit >> 5; b = bh >> 2; h = bh & 3; q0 = qb * 256; wq = wave; map = 0; }
;         else { const int qb = unit & 63; bh = unit >> 6; b = bh >> 3; h = bh & 7; q0 = qb * 128; wq = wave & 3; map = wave >> 2; }
;         const size_t rowbase = (size_t)b * SEQ;
;         const size_t qrow = rowbase + q0 + 32 * wq + r;
;         bf16x8 qf[NKS];
;         {
;             const bf16* qp = MODE == 0 ? Qp + qrow * 768 + h * 192 + 8 * hh : Qp + qrow * 1024 + (2 * h + map) * 64 + 8 * hh;
; #pragma unroll
;             for (int ks = 0; ks < NKS; ++ks) qf[ks] = *(const bf16x8*)(qp + 16 * ks);
;         }
;         const bf16* kp[NKI]; int kadv[NKI];
; #pragma unroll
;         for (int n = 0; n < NKI; ++n) {
;             const int P = 64 * (wave + 8 * n) + lane;
;             if (MODE == 0) {
;                 const int row = P / 24, cp = P - row * 24, c = (cp & ~7) | ((cp & 7) ^ ((row >> 1) & 7));
;                 if (c < 16) { kp[n] = Kp + (rowbase + row) * 512 + h * 128 + c * 8; kadv[n] = 64 * 512; }
;                 else { kp[n] = KPEp + (rowbase + row) * 64 + (c - 16) * 8; kadv[n] = 64 * 64; }
;             } else {
;                 const int row = P >> 4, c = (P & 15) ^ (row & 15);
;                 kp[n] = Kp + (rowbase + row) * 1024 + h * 128 + c * 8; kadv[n] = 64 * 1024;
;             }
;         }
;         const bf16* vp[2];
; #pragma unroll
;         for (int n = 0; n < 2; ++n) { const int P = 64 * (wave + 8 * n) + lane, dv = P >> 3, c = (P & 7) ^ ((dv >> 1) & 7); vp[n] = Vtp + ((size_t)(bh * 128 + dv)) * SEQ + c * 8; }
;         const unsigned kdma = lds0 + wave * 1024, vdma = lds0 + 3 * KB + wave * 1024;
;     ...
;         const int ka = MODE == 0 ? r * RB + ((hh ^ ((r >> 1) & 7)) * 16) : r * RB + (((map * 8 + hh) ^ (r & 15)) * 16);
;         const int va = r * 128 + ((hh ^ ((r >> 1) & 7)) * 16);
;         const LAS unsigned char* vring = lds + 3 * KB;
;         f32x16 o[4], S0, S1;
.LBB0_759:
	v_mov_b32_e32 v76, v235
	s_lshl_b32 s9, s0, 7
	v_readfirstlane_b32 s16, v76
	s_ashr_i32 s3, s16, 6
	s_and_b32 s19, s3, 3
	s_ashr_i32 s10, s0, 9
	s_and_b32 s9, s9, 0x1f80
	s_lshl_b32 s17, s19, 5
	v_and_b32_e32 v4, 31, v76
	s_ashr_i32 s11, s10, 31
	s_or_b32 s9, s17, s9
	s_ashr_i32 s18, s16, 8
	s_lshl_b64 s[10:11], s[10:11], 13
	v_or_b32_e32 v0, s9, v4
	s_lshl_b32 s9, s0, 1
	v_or_b32_e32 v0, s10, v0
	v_mov_b32_e32 v1, s11
	s_and_b32 s20, s9, 0xffffff80
	s_and_b32 s17, s9, 0x380
	s_lshl_b32 s9, s18, 6
	v_lshlrev_b64 v[172:173], 10, v[0:1]
	v_lshlrev_b64 v[0:1], 11, v[0:1]
	s_add_i32 s38, s9, s17
	v_bfe_u32 v253, v76, 5, 1
	v_lshl_add_u64 v[0:1], s[54:55], 0, v[0:1]
	s_ashr_i32 s39, s38, 31
	v_lshl_add_u64 v[0:1], s[38:39], 1, v[0:1]
	v_lshlrev_b32_e32 v232, 4, v253
	v_lshl_add_u64 v[0:1], v[0:1], 0, v[232:233]
	global_load_dwordx4 v[108:111], v[0:1], off
	global_load_dwordx4 v[104:107], v[0:1], off offset:32
	global_load_dwordx4 v[100:103], v[0:1], off offset:64
	global_load_dwordx4 v[96:99], v[0:1], off offset:96
	v_mov_b32_e32 v0, s16
	s_movk_i32 s9, 0xffc0
	v_bfi_b32 v2, s9, v0, v76
	v_ashrrev_i32_e32 v0, 4, v2
	s_and_b32 s8, s5, 0xffffff80
	s_lshl_b32 s9, s17, 1
	v_ashrrev_i32_e32 v1, 31, v0
	s_add_u32 s38, s1, s9
	v_xor_b32_e32 v3, v0, v76
	v_lshl_add_u64 v[0:1], s[10:11], 0, v[0:1]
	s_addc_u32 s39, s4, 0
	v_lshlrev_b64 v[0:1], 11, v[0:1]
	v_lshlrev_b32_e32 v3, 4, v3
	v_lshl_add_u64 v[0:1], s[38:39], 0, v[0:1]
	v_and_b32_e32 v232, 0xf0, v3
	v_add_u32_e32 v3, 0x200, v2
	v_lshl_add_u64 v[48:49], v[0:1], 0, v[232:233]
	v_ashrrev_i32_e32 v0, 4, v3
	v_ashrrev_i32_e32 v1, 31, v0
	v_xor_b32_e32 v5, v0, v76
	v_lshl_add_u64 v[0:1], s[10:11], 0, v[0:1]
	s_lshl_b32 s3, s3, 10
	v_lshlrev_b64 v[0:1], 11, v[0:1]
	v_lshlrev_b32_e32 v5, 4, v5
	v_lshrrev_b32_e32 v78, 4, v2
	s_add_i32 s58, s3, 0
	s_lshl_b32 s3, s18, 3
	v_and_b32_e32 v6, 15, v76
	v_lshl_add_u64 v[0:1], s[38:39], 0, v[0:1]
	v_and_b32_e32 v232, 0xf0, v5
	v_ashrrev_i32_e32 v77, 3, v2
	v_xor_b32_e32 v2, v78, v76
	v_lshlrev_b32_e32 v5, 8, v4
	v_bitop3_b32 v6, s3, v6, v253 bitop3:0x36
	v_lshl_add_u64 v[50:51], v[0:1], 0, v[232:233]
	v_add_u32_e32 v0, s20, v77
	v_lshlrev_b32_e32 v2, 4, v2
	v_ashrrev_i32_e32 v79, 3, v3
	v_lshl_add_u32 v132, v6, 4, v5
	v_lshrrev_b32_e32 v5, 1, v76
	v_subrev_u32_e32 v60, s1, v48
	v_lshrrev_b32_e32 v61, 3, v60
	v_and_b32_e32 v61, 0x1fff00, v61
	v_bfe_u32 v62, v60, 8, 3
	v_lshl_or_b32 v61, v62, 21, v61
	v_and_b32_e32 v60, 0x30000ff, v60
	v_or_b32_e32 v60, v60, v61
	v_mov_b32_e32 v49, s4
	v_add_co_u32_e32 v48, vcc, s1, v60
	s_nop 1
	v_addc_co_u32_e32 v49, vcc, 0, v49, vcc
	v_subrev_u32_e32 v60, s1, v50
	v_lshrrev_b32_e32 v61, 3, v60
	v_and_b32_e32 v61, 0x1fff00, v61
	v_bfe_u32 v62, v60, 8, 3
	v_lshl_or_b32 v61, v62, 21, v61
	v_and_b32_e32 v60, 0x30000ff, v60
	v_or_b32_e32 v60, v60, v61
	v_mov_b32_e32 v51, s4
	v_add_co_u32_e32 v50, vcc, s1, v60
	s_nop 1
	v_addc_co_u32_e32 v51, vcc, 0, v51, vcc
	s_mov_b32 s3, m0
	s_mov_b32 m0, s58
	s_nop 0
	global_load_lds_dwordx4 v[48:49], off
	s_mov_b32 m0, s3
	v_ashrrev_i32_e32 v1, 31, v0
	v_and_b32_e32 v232, 0x70, v2
	v_add_u32_e32 v2, s20, v79
	v_bitop3_b32 v5, v253, v5, 7 bitop3:0x78
	s_add_i32 s59, s58, 0x2000
	s_mov_b32 s3, m0
	s_mov_b32 m0, s59
	s_nop 0
	global_load_lds_dwordx4 v[50:51], off
	s_mov_b32 m0, s3
	s_mov_b64 s[10:11], 0x4000
	v_lshlrev_b64 v[0:1], 14, v[0:1]
	v_ashrrev_i32_e32 v3, 31, v2
	v_lshlrev_b32_e32 v80, 4, v5
	v_lshlrev_b32_e32 v81, 7, v4
	v_lshl_add_u64 v[4:5], v[48:49], 0, s[10:11]
	s_add_i32 s3, s58, 0x4000
	s_mov_b32 s9, m0
	s_mov_b32 m0, s3
	s_nop 0
	global_load_lds_dwordx4 v[4:5], off
	s_mov_b32 m0, s9
	v_lshl_add_u64 v[0:1], s[72:73], 0, v[0:1]
	v_lshlrev_b64 v[2:3], 14, v[2:3]
	v_lshl_add_u64 v[6:7], v[50:51], 0, s[10:11]
	s_add_i32 s3, s58, 0x6000
	s_mov_b32 s9, m0
	s_mov_b32 m0, s3
	s_nop 0
	global_load_lds_dwordx4 v[6:7], off
	s_mov_b32 m0, s9
	v_lshl_add_u64 v[0:1], v[0:1], 0, v[232:233]
	v_lshl_add_u64 v[2:3], s[72:73], 0, v[2:3]
	s_add_i32 s65, s58, 0x10000
	s_mov_b32 s3, m0
	s_mov_b32 m0, s65
	s_nop 0
	global_load_lds_dwordx4 v[0:1], off
	s_mov_b32 m0, s3
	v_lshl_add_u64 v[2:3], v[2:3], 0, v[232:233]
	s_add_i32 s3, s58, 0x12000
	s_mov_b32 s9, m0
	s_mov_b32 m0, s3
	s_nop 0
	global_load_lds_dwordx4 v[2:3], off
	s_mov_b32 m0, s9
	v_xor_b32_e32 v137, 32, v132
	v_xor_b32_e32 v138, 64, v132
	v_xor_b32_e32 v139, 0x60, v132
	v_subrev_u32_e32 v128, s1, v48
	v_subrev_u32_e32 v129, s1, v50
	v_subrev_u32_e32 v130, s72, v0
	v_subrev_u32_e32 v131, s72, v2
	v_or_b32_e32 v176, v80, v81
	v_xor_b32_e32 v177, 32, v176
	v_xor_b32_e32 v178, 64, v176
	v_xor_b32_e32 v179, 0x60, v176
	v_add_u32_e32 v216, 0x10000, v176
	v_add_u32_e32 v217, 0x10000, v177
	v_add_u32_e32 v218, 0x10000, v178
	v_add_u32_e32 v219, 0x10000, v179
	v_mov_b32_e32 v234, v235
	v_and_b32_e32 v235, 63, v76
	s_mov_b32 s42, m0
	s_add_u32 s8, s1, 0x8000
	s_addc_u32 s9, s4, 0
	s_add_u32 s10, s72, 0x80
	s_addc_u32 s11, s73, 0
	s_mov_b32 s41, 0
	s_waitcnt vmcnt(0) lgkmcnt(0)
	s_barrier
; #define ATT_DMA_K(slotoff) do { _Pragma("unroll") for (int n = 0; n < NKI; ++n) glds16(kp[n], (unsigned)__builtin_amdgcn_readfirstlane(kdma + (slotoff) + n * 8192)); } while (0)
; #define ATT_DMA_V(slotoff) do { _Pragma("unroll") for (int n = 0; n < 2; ++n) glds16(vp[n], (unsigned)__builtin_amdgcn_readfirstlane(vdma + (slotoff) + n * 8192)); } while (0)
; #define ATT_ADV_K() do { _Pragma("unroll") for (int n = 0; n < NKI; ++n) kp[n] += kadv[n]; } while (0)
; #define ATT_ADV_V() do { _Pragma("unroll") for (int n = 0; n < 2; ++n) vp[n] += 64; } while (0)
; template <int MODE>
; __device__ __forceinline__ void attn_phase(LAS unsigned char* lds, const bf16* Qp, const bf16* Kp, const bf16* KPEp, const bf16* Vtp, bf16* CAT, float lam, int vcu, int G) {
;     ...
; #pragma unroll
;         for (int db = 0; db < 4; ++db)
; #pragma unroll
;             for (int i = 0; i < 16; ++i) o[db][i] = 0.f;
;         float mhat = 0.f, lrun = 0.f, fpend = 1.f; bool havepend = false;
;         ATT_DMA_K(0); ATT_ADV_K(); ATT_DMA_K(KB); ATT_ADV_K(); ATT_DMA_V(0); ATT_ADV_V();
;         asm volatile("s_waitcnt vmcnt(0) lgkmcnt(0)\n\ts_barrier" ::: "memory");
;         int kr = 0, kw = 2 * KB, vr = 2 * VB, vw = VB;
;         if constexpr (MODE == 1) {
;             bf16x8 pfB[4];
;             bf16x8 kf[8], vf[8], vg[8];
;             float fp = 1.f; bool pend = false;
;     ...
;             ATT1_ITER(pfB, pf, 0, false);
	ds_read_b128 v[140:143], v132
	ds_read_b128 v[144:147], v137
	ds_read_b128 v[148:151], v138
	ds_read_b128 v[152:155], v139
	ds_read_b128 v[156:159], v132 offset:8192
	ds_read_b128 v[160:163], v137 offset:8192
	ds_read_b128 v[164:167], v138 offset:8192
	ds_read_b128 v[168:171], v139 offset:8192
	v_mov_b64_e32 v[0:1], 0
	v_mov_b64_e32 v[2:3], 0
	v_mov_b64_e32 v[4:5], 0
	v_mov_b64_e32 v[6:7], 0
	v_mov_b64_e32 v[8:9], 0
	v_mov_b64_e32 v[10:11], 0
	v_mov_b64_e32 v[12:13], 0
	v_mov_b64_e32 v[14:15], 0
	v_mov_b64_e32 v[16:17], 0
	v_mov_b64_e32 v[18:19], 0
	v_mov_b64_e32 v[20:21], 0
	v_mov_b64_e32 v[22:23], 0
	v_mov_b64_e32 v[24:25], 0
	v_mov_b64_e32 v[26:27], 0
	v_mov_b64_e32 v[28:29], 0
	v_mov_b64_e32 v[30:31], 0
	v_mov_b64_e32 v[32:33], 0
	v_mov_b64_e32 v[34:35], 0
	v_mov_b64_e32 v[36:37], 0
	v_mov_b64_e32 v[38:39], 0
	v_mov_b64_e32 v[40:41], 0
	v_mov_b64_e32 v[42:43], 0
	v_mov_b64_e32 v[44:45], 0
	v_mov_b64_e32 v[46:47], 0
	v_mov_b64_e32 v[48:49], 0
	v_mov_b64_e32 v[50:51], 0
	v_mov_b64_e32 v[52:53], 0
	v_mov_b64_e32 v[54:55], 0
	v_mov_b64_e32 v[56:57], 0
	v_mov_b64_e32 v[58:59], 0
	v_mov_b64_e32 v[60:61], 0
	v_mov_b64_e32 v[62:63], 0
	s_waitcnt lgkmcnt(7)
	v_mfma_f32_32x32x16_bf16 v[64:79], v[140:143], v[108:111], 0
	s_add_i32 m0, s58, 0x8000
	s_nop 0
	global_load_lds_dwordx4 v128, s[8:9]
	s_waitcnt lgkmcnt(6)
	v_mfma_f32_32x32x16_bf16 v[64:79], v[144:147], v[104:107], v[64:79]
	s_add_i32 m0, s58, 0xa000
	s_nop 0
	global_load_lds_dwordx4 v129, s[8:9]
	s_waitcnt lgkmcnt(5)
	v_mfma_f32_32x32x16_bf16 v[64:79], v[148:151], v[100:103], v[64:79]
	s_add_u32 s8, s8, 0x4000
	s_addc_u32 s9, s9, 0
	s_waitcnt lgkmcnt(4)
	v_mfma_f32_32x32x16_bf16 v[64:79], v[152:155], v[96:99], v[64:79]
	s_add_i32 m0, s65, 0x4000
	s_nop 0
	global_load_lds_dwordx4 v130, s[10:11]
	s_waitcnt lgkmcnt(3)
	v_mfma_f32_32x32x16_bf16 v[80:95], v[156:159], v[108:111], 0
	s_add_i32 m0, s65, 0x6000
	s_nop 0
	global_load_lds_dwordx4 v131, s[10:11]
	s_waitcnt lgkmcnt(2)
	v_mfma_f32_32x32x16_bf16 v[80:95], v[160:163], v[104:107], v[80:95]
	s_add_u32 s10, s10, 0x80
	s_addc_u32 s11, s11, 0
	s_waitcnt lgkmcnt(1)
	v_mfma_f32_32x32x16_bf16 v[80:95], v[164:167], v[100:103], v[80:95]
	s_waitcnt lgkmcnt(0)
	v_mfma_f32_32x32x16_bf16 v[80:95], v[168:171], v[96:99], v[80:95]
	s_nop 11
	v_max3_f32 v224, v64, v65, v66
	v_max3_f32 v225, v67, v68, v69
	v_max3_f32 v224, v224, v70, v71
	v_max3_f32 v225, v225, v72, v73
	v_max3_f32 v224, v224, v74, v75
	v_max3_f32 v225, v225, v76, v77
	v_max3_f32 v224, v224, v78, v79
	v_max3_f32 v224, v224, v80, v81
	v_max3_f32 v225, v225, v82, v83
	v_max3_f32 v224, v224, v84, v85
	v_max3_f32 v225, v225, v86, v87
	v_max3_f32 v224, v224, v88, v89
	v_max3_f32 v225, v225, v90, v91
	v_max3_f32 v224, v224, v92, v93
	v_max3_f32 v225, v225, v94, v95
	v_max_f32_e32 v224, v224, v225
	v_mov_b32_e32 v225, v224
	s_nop 1
	v_permlane32_swap_b32_e32 v224, v225
	v_max_f32_e32 v224, v224, v225
	v_sub_f32_e32 v236, 0, v224
	v_sub_f32_e32 v237, 0, v224
	v_sub_f32_e32 v238, 0, v224
	v_sub_f32_e32 v239, 0, v224
	v_sub_f32_e32 v240, 0, v224
	v_sub_f32_e32 v241, 0, v224
	v_sub_f32_e32 v242, 0, v224
	v_sub_f32_e32 v243, 0, v224
	v_sub_f32_e32 v244, 0, v224
	v_sub_f32_e32 v245, 0, v224
	v_sub_f32_e32 v246, 0, v224
	v_sub_f32_e32 v247, 0, v224
	v_sub_f32_e32 v248, 0, v224
	v_sub_f32_e32 v249, 0, v224
	v_sub_f32_e32 v250, 0, v224
	v_sub_f32_e32 v251, 0, v224
	v_sub_f32_e32 v64, v64, v224
	v_sub_f32_e32 v65, v65, v224
	v_sub_f32_e32 v66, v66, v224
	v_sub_f32_e32 v67, v67, v224
	v_sub_f32_e32 v68, v68, v224
	v_sub_f32_e32 v69, v69, v224
	v_sub_f32_e32 v70, v70, v224
	v_sub_f32_e32 v71, v71, v224
	v_sub_f32_e32 v72, v72, v224
	v_sub_f32_e32 v73, v73, v224
	v_sub_f32_e32 v74, v74, v224
	v_sub_f32_e32 v75, v75, v224
	v_sub_f32_e32 v76, v76, v224
	v_sub_f32_e32 v77, v77, v224
	v_sub_f32_e32 v78, v78, v224
	v_sub_f32_e32 v79, v79, v224
	v_sub_f32_e32 v80, v80, v224
	v_sub_f32_e32 v81, v81, v224
	v_sub_f32_e32 v82, v82, v224
	v_sub_f32_e32 v83, v83, v224
	v_sub_f32_e32 v84, v84, v224
	v_sub_f32_e32 v85, v85, v224
	v_sub_f32_e32 v86, v86, v224
	v_sub_f32_e32 v87, v87, v224
	v_sub_f32_e32 v88, v88, v224
	v_sub_f32_e32 v89, v89, v224
	v_sub_f32_e32 v90, v90, v224
	v_sub_f32_e32 v91, v91, v224
	v_sub_f32_e32 v92, v92, v224
	v_sub_f32_e32 v93, v93, v224
	v_sub_f32_e32 v94, v94, v224
	v_sub_f32_e32 v95, v95, v224
	v_mov_b32_e32 v133, 0
	v_mov_b32_e32 v136, 0
	v_exp_f32_e32 v64, v64
	v_exp_f32_e32 v65, v65
	v_add_f32_e32 v133, v133, v64
	v_add_f32_e32 v136, v136, v65
	v_exp_f32_e32 v66, v66
	v_exp_f32_e32 v67, v67
	v_add_f32_e32 v133, v133, v66
	v_add_f32_e32 v136, v136, v67
	v_exp_f32_e32 v68, v68
	v_exp_f32_e32 v69, v69
	v_add_f32_e32 v133, v133, v68
	v_add_f32_e32 v136, v136, v69
	v_exp_f32_e32 v70, v70
	v_exp_f32_e32 v71, v71
	v_add_f32_e32 v133, v133, v70
	v_add_f32_e32 v136, v136, v71
	v_exp_f32_e32 v72, v72
	v_exp_f32_e32 v73, v73
	v_add_f32_e32 v133, v133, v72
	v_add_f32_e32 v136, v136, v73
	v_exp_f32_e32 v74, v74
	v_exp_f32_e32 v75, v75
	v_add_f32_e32 v133, v133, v74
	v_add_f32_e32 v136, v136, v75
	v_exp_f32_e32 v76, v76
	v_exp_f32_e32 v77, v77
	v_add_f32_e32 v133, v133, v76
	v_add_f32_e32 v136, v136, v77
	v_exp_f32_e32 v78, v78
	v_exp_f32_e32 v79, v79
	v_add_f32_e32 v133, v133, v78
	v_add_f32_e32 v136, v136, v79
	v_cvt_pk_bf16_f32 v112, v64, v65
	v_cvt_pk_bf16_f32 v113, v66, v67
	v_cvt_pk_bf16_f32 v114, v68, v69
	v_cvt_pk_bf16_f32 v115, v70, v71
	v_cvt_pk_bf16_f32 v116, v72, v73
	v_cvt_pk_bf16_f32 v117, v74, v75
	v_cvt_pk_bf16_f32 v118, v76, v77
	v_cvt_pk_bf16_f32 v119, v78, v79
	s_mov_b32 s66, 0
	s_waitcnt vmcnt(0) lgkmcnt(0)
	s_barrier
; #define LAS __attribute__((address_space(3)))
; #define MFMA32(a, b, c) __builtin_amdgcn_mfma_f32_32x32x16_bf16((a), (b), (c), 0, 0, 0)
; __device__ __forceinline__ void att1_load(bf16x8 (&kf)[8], bf16x8 (&vf)[8], const LAS unsigned char* kslot, int ka, const LAS unsigned char* vslot, int va) {
; #pragma unroll
;     for (int ks = 0; ks < 4; ++ks) { const LAS unsigned char* p = kslot + (ka ^ (ks * 32)); kf[2 * ks] = *(const LAS bf16x8*)p; kf[2 * ks + 1] = *(const LAS bf16x8*)(p + 32 * 256); }
; #pragma unroll
;     for (int kk = 0; kk < 2; ++kk)
; #pragma unroll
;         for (int db = 0; db < 4; ++db) vf[kk * 4 + db] = *(const LAS bf16x8*)(vslot + ((va ^ (kk * 32)) + db * 4096));
; }
; __device__ __forceinline__ void att1_load2(bf16x8 (&vg)[8], const LAS unsigned char* vslot, int va) {
; #pragma unroll
;     for (int kk = 2; kk < 4; ++kk)
; #pragma unroll
;         for (int db = 0; db < 4; ++db) vg[(kk - 2) * 4 + db] = *(const LAS bf16x8*)(vslot + ((va ^ (kk * 32)) + db * 4096));
; }
; __device__ __forceinline__ void att1_qk(f32x16& s0, f32x16& s1, const bf16x8 (&kf)[8], const bf16x8 (&qf)[4]) {
;     f32x16 z;
; #pragma unroll
;     for (int i = 0; i < 16; ++i) z[i] = 0.f;
;     s0 = MFMA32(kf[0], qf[0], z); s1 = MFMA32(kf[1], qf[0], z);
; #pragma unroll
;     for (int ks = 1; ks < 4; ++ks) { s0 = MFMA32(kf[2 * ks], qf[ks], s0); s1 = MFMA32(kf[2 * ks + 1], qf[ks], s1); }
; }
; __device__ __forceinline__ void att1_pv(f32x16 (&o)[4], const bf16x8 (&vf)[8], const bf16x8 (&vg)[8], const bf16x8 (&pf)[4]) {
; #pragma unroll
;     for (int kk = 0; kk < 2; ++kk)
; #pragma unroll
;         for (int db = 0; db < 4; ++db) o[db] = MFMA32(vf[kk * 4 + db], pf[kk], o[db]);
; #pragma unroll
;     for (int kk = 2; kk < 4; ++kk)
; #pragma unroll
;         for (int db = 0; db < 4; ++db) o[db] = MFMA32(vg[(kk - 2) * 4 + db], pf[kk], o[db]);
; }
; template <int MODE>
; __device__ __forceinline__ void attn_phase(LAS unsigned char* lds, const bf16* Qp, const bf16* Kp, const bf16* KPEp, const bf16* Vtp, bf16* CAT, float lam, int vcu, int G) {
;     ...
;             ATT1_ITER(pfB, pf, 0, false);
;             for (int i2 = 1; i2 < 127; i2 += 2) {
;                 ATT1_ITER(pf, pfB, i2, true);
;                 ATT1_ITER(pfB, pf, i2 + 1, true);
.Lda_loop:
	ds_read_b128 v[140:143], v132 offset:16384
	ds_read_b128 v[144:147], v137 offset:16384
	ds_read_b128 v[148:151], v138 offset:16384
	ds_read_b128 v[152:155], v139 offset:16384
	ds_read_b128 v[156:159], v132 offset:24576
	ds_read_b128 v[160:163], v137 offset:24576
	ds_read_b128 v[164:167], v138 offset:24576
	ds_read_b128 v[168:171], v139 offset:24576
	ds_read_b128 v[184:187], v216
	ds_read_b128 v[188:191], v216 offset:4096
	ds_read_b128 v[192:195], v216 offset:8192
	ds_read_b128 v[196:199], v216 offset:12288
	v_exp_f32_e32 v80, v80
	v_exp_f32_e32 v81, v81
	v_add_f32_e32 v133, v133, v80
	v_add_f32_e32 v136, v136, v81
	v_exp_f32_e32 v82, v82
	v_exp_f32_e32 v83, v83
	v_add_f32_e32 v133, v133, v82
	v_add_f32_e32 v136, v136, v83
	s_waitcnt lgkmcnt(8)
	v_mfma_f32_32x32x16_bf16 v[64:79], v[140:143], v[108:111], v[236:251]
	v_exp_f32_e32 v84, v84
	v_exp_f32_e32 v85, v85
	v_add_f32_e32 v133, v133, v84
	v_add_f32_e32 v136, v136, v85
	ds_read_b128 v[200:203], v217
	v_mfma_f32_32x32x16_bf16 v[64:79], v[144:147], v[104:107], v[64:79]
	v_exp_f32_e32 v86, v86
	v_exp_f32_e32 v87, v87
	v_add_f32_e32 v133, v133, v86
	v_add_f32_e32 v136, v136, v87
	ds_read_b128 v[204:207], v217 offset:4096
	v_mfma_f32_32x32x16_bf16 v[64:79], v[148:151], v[100:103], v[64:79]
	v_exp_f32_e32 v88, v88
	v_exp_f32_e32 v89, v89
	v_add_f32_e32 v133, v133, v88
	v_add_f32_e32 v136, v136, v89
	v_cvt_pk_bf16_f32 v120, v80, v81
	v_cvt_pk_bf16_f32 v121, v82, v83
	ds_read_b128 v[208:211], v217 offset:8192
	v_mfma_f32_32x32x16_bf16 v[64:79], v[152:155], v[96:99], v[64:79]
	v_exp_f32_e32 v90, v90
	v_exp_f32_e32 v91, v91
	v_add_f32_e32 v133, v133, v90
	v_add_f32_e32 v136, v136, v91
	v_cvt_pk_bf16_f32 v122, v84, v85
	v_cvt_pk_bf16_f32 v123, v86, v87
	ds_read_b128 v[212:215], v217 offset:12288
	s_waitcnt lgkmcnt(4)
	v_mfma_f32_32x32x16_bf16 v[48:63], v[184:187], v[112:115], v[48:63]
	v_exp_f32_e32 v92, v92
	v_exp_f32_e32 v93, v93
	v_add_f32_e32 v133, v133, v92
	v_add_f32_e32 v136, v136, v93
	ds_read_b128 v[140:143], v218
	v_mfma_f32_32x32x16_bf16 v[32:47], v[188:191], v[112:115], v[32:47]
	v_exp_f32_e32 v94, v94
	v_exp_f32_e32 v95, v95
	v_add_f32_e32 v133, v133, v94
	v_add_f32_e32 v136, v136, v95
	ds_read_b128 v[144:147], v218 offset:4096
	v_mfma_f32_32x32x16_bf16 v[16:31], v[192:195], v[112:115], v[16:31]
	v_cvt_pk_bf16_f32 v124, v88, v89
	v_cvt_pk_bf16_f32 v125, v90, v91
	ds_read_b128 v[148:151], v218 offset:8192
	v_mfma_f32_32x32x16_bf16 v[0:15], v[196:199], v[112:115], v[0:15]
	v_cvt_pk_bf16_f32 v126, v92, v93
	v_cvt_pk_bf16_f32 v127, v94, v95
	ds_read_b128 v[152:155], v218 offset:12288
	v_max3_f32 v224, v64, v65, v66
	v_max3_f32 v225, v67, v68, v69
	v_max3_f32 v224, v224, v70, v71
	v_mfma_f32_32x32x16_bf16 v[80:95], v[156:159], v[108:111], v[236:251]
	s_add_i32 m0, s58, 0xc000
	v_max3_f32 v225, v225, v72, v73
	global_load_lds_dwordx4 v128, s[8:9]
	s_add_i32 m0, s58, 0xe000
	s_nop 0
	global_load_lds_dwordx4 v129, s[8:9]
	s_add_u32 s8, s8, 0x4000
	s_addc_u32 s9, s9, 0
	v_mfma_f32_32x32x16_bf16 v[80:95], v[160:163], v[104:107], v[80:95]
	s_add_i32 m0, s58, 0x0
	v_max3_f32 v224, v224, v74, v75
	global_load_lds_dwordx4 v128, s[8:9]
	s_add_i32 m0, s58, 0x2000
	ds_read_b128 v[156:159], v219
	global_load_lds_dwordx4 v129, s[8:9]
	s_add_u32 s8, s8, 0x4000
	s_addc_u32 s9, s9, 0
	v_mfma_f32_32x32x16_bf16 v[80:95], v[164:167], v[100:103], v[80:95]
	s_add_i32 m0, s65, 0x8000
	v_max3_f32 v225, v225, v76, v77
	global_load_lds_dwordx4 v130, s[10:11]
	s_add_i32 m0, s65, 0xa000
	ds_read_b128 v[160:163], v219 offset:4096
	global_load_lds_dwordx4 v131, s[10:11]
	s_add_u32 s10, s10, 0x80
	s_addc_u32 s11, s11, 0
	v_mfma_f32_32x32x16_bf16 v[80:95], v[168:171], v[96:99], v[80:95]
	s_add_i32 m0, s65, 0xc000
	v_max3_f32 v224, v224, v78, v79
	global_load_lds_dwordx4 v130, s[10:11]
	s_add_i32 m0, s65, 0xe000
	ds_read_b128 v[164:167], v219 offset:8192
	global_load_lds_dwordx4 v131, s[10:11]
	s_add_u32 s10, s10, 0x80
	s_addc_u32 s11, s11, 0
	s_waitcnt lgkmcnt(7)
	v_mfma_f32_32x32x16_bf16 v[48:63], v[200:203], v[116:119], v[48:63]
	ds_read_b128 v[168:171], v219 offset:12288
	v_mfma_f32_32x32x16_bf16 v[32:47], v[204:207], v[116:119], v[32:47]
	s_nop 1
	v_max3_f32 v224, v224, v80, v81
	v_max3_f32 v225, v225, v82, v83
	v_max3_f32 v224, v224, v84, v85
	v_max3_f32 v225, v225, v86, v87
	v_mfma_f32_32x32x16_bf16 v[16:31], v[208:211], v[116:119], v[16:31]
	v_max3_f32 v224, v224, v88, v89
	v_max3_f32 v225, v225, v90, v91
	v_max3_f32 v224, v224, v92, v93
	v_max3_f32 v225, v225, v94, v95
	v_max_f32_e32 v224, v224, v225
	v_mov_b32_e32 v225, v224
	s_nop 1
	v_permlane32_swap_b32_e32 v224, v225
	v_max_f32_e32 v224, v224, v225
	v_cmp_lt_f32_e32 vcc, 0x41000000, v224
	v_mfma_f32_32x32x16_bf16 v[0:15], v[212:215], v[116:119], v[0:15]
	s_nop 1
	s_cmp_lg_u64 vcc, 0
	s_cbranch_scc1 .Lda_rareA_0a

; #define LAS __attribute__((address_space(3)))
; #define MFMA32(a, b, c) __builtin_amdgcn_mfma_f32_32x32x16_bf16((a), (b), (c), 0, 0, 0)
; __device__ __forceinline__ void att1_load(bf16x8 (&kf)[8], bf16x8 (&vf)[8], const LAS unsigned char* kslot, int ka, const LAS unsigned char* vslot, int va) {
; #pragma unroll
;     for (int ks = 0; ks < 4; ++ks) { const LAS unsigned char* p = kslot + (ka ^ (ks * 32)); kf[2 * ks] = *(const LAS bf16x8*)p; kf[2 * ks + 1] = *(const LAS bf16x8*)(p + 32 * 256); }
; #pragma unroll
;     for (int kk = 0; kk < 2; ++kk)
; #pragma unroll
;         for (int db = 0; db < 4; ++db) vf[kk * 4 + db] = *(const LAS bf16x8*)(vslot + ((va ^ (kk * 32)) + db * 4096));
; }
; __device__ __forceinline__ void att1_load2(bf16x8 (&vg)[8], const LAS unsigned char* vslot, int va) {
; #pragma unroll
;     for (int kk = 2; kk < 4; ++kk)
; #pragma unroll
;         for (int db = 0; db < 4; ++db) vg[(kk - 2) * 4 + db] = *(const LAS bf16x8*)(vslot + ((va ^ (kk * 32)) + db * 4096));
; }
; __device__ __forceinline__ void att1_qk(f32x16& s0, f32x16& s1, const bf16x8 (&kf)[8], const bf16x8 (&qf)[4]) {
;     f32x16 z;
; #pragma unroll
;     for (int i = 0; i < 16; ++i) z[i] = 0.f;
;     s0 = MFMA32(kf[0], qf[0], z); s1 = MFMA32(kf[1], qf[0], z);
; #pragma unroll
;     for (int ks = 1; ks < 4; ++ks) { s0 = MFMA32(kf[2 * ks], qf[ks], s0); s1 = MFMA32(kf[2 * ks + 1], qf[ks], s1); }
; }
; __device__ __forceinline__ void att1_pv(f32x16 (&o)[4], const bf16x8 (&vf)[8], const bf16x8 (&vg)[8], const bf16x8 (&pf)[4]) {
; #pragma unroll
;     for (int kk = 0; kk < 2; ++kk)
; #pragma unroll
;         for (int db = 0; db < 4; ++db) o[db] = MFMA32(vf[kk * 4 + db], pf[kk], o[db]);
; #pragma unroll
;     for (int kk = 2; kk < 4; ++kk)
; #pragma unroll
;         for (int db = 0; db < 4; ++db) o[db] = MFMA32(vg[(kk - 2) * 4 + db], pf[kk], o[db]);
; }
.Lda_skipB_0a:
	ds_read_b128 v[140:143], v132 offset:32768
	ds_read_b128 v[144:147], v137 offset:32768
	ds_read_b128 v[148:151], v138 offset:32768
	ds_read_b128 v[152:155], v139 offset:32768
	ds_read_b128 v[156:159], v132 offset:40960
	ds_read_b128 v[160:163], v137 offset:40960
	ds_read_b128 v[164:167], v138 offset:40960
	ds_read_b128 v[168:171], v139 offset:40960
	ds_read_b128 v[184:187], v216 offset:16384
	ds_read_b128 v[188:191], v216 offset:20480
	ds_read_b128 v[192:195], v216 offset:24576
	ds_read_b128 v[196:199], v216 offset:28672
	v_exp_f32_e32 v80, v80
	v_exp_f32_e32 v81, v81
	v_add_f32_e32 v133, v133, v80
	v_add_f32_e32 v136, v136, v81
	v_exp_f32_e32 v82, v82
	v_exp_f32_e32 v83, v83
	v_add_f32_e32 v133, v133, v82
	v_add_f32_e32 v136, v136, v83
	s_waitcnt lgkmcnt(8)
	v_mfma_f32_32x32x16_bf16 v[64:79], v[140:143], v[108:111], v[236:251]
	v_exp_f32_e32 v84, v84
	v_exp_f32_e32 v85, v85
	v_add_f32_e32 v133, v133, v84
	v_add_f32_e32 v136, v136, v85
	ds_read_b128 v[200:203], v217 offset:16384
	v_mfma_f32_32x32x16_bf16 v[64:79], v[144:147], v[104:107], v[64:79]
	v_exp_f32_e32 v86, v86
	v_exp_f32_e32 v87, v87
	v_add_f32_e32 v133, v133, v86
	v_add_f32_e32 v136, v136, v87
	ds_read_b128 v[204:207], v217 offset:20480
	v_mfma_f32_32x32x16_bf16 v[64:79], v[148:151], v[100:103], v[64:79]
	v_exp_f32_e32 v88, v88
	v_exp_f32_e32 v89, v89
	v_add_f32_e32 v133, v133, v88
	v_add_f32_e32 v136, v136, v89
	v_cvt_pk_bf16_f32 v120, v80, v81
	v_cvt_pk_bf16_f32 v121, v82, v83
	ds_read_b128 v[208:211], v217 offset:24576
	v_mfma_f32_32x32x16_bf16 v[64:79], v[152:155], v[96:99], v[64:79]
	v_exp_f32_e32 v90, v90
	v_exp_f32_e32 v91, v91
	v_add_f32_e32 v133, v133, v90
	v_add_f32_e32 v136, v136, v91
	v_cvt_pk_bf16_f32 v122, v84, v85
	v_cvt_pk_bf16_f32 v123, v86, v87
	ds_read_b128 v[212:215], v217 offset:28672
	s_waitcnt lgkmcnt(4)
	v_mfma_f32_32x32x16_bf16 v[48:63], v[184:187], v[112:115], v[48:63]
	v_exp_f32_e32 v92, v92
	v_exp_f32_e32 v93, v93
	v_add_f32_e32 v133, v133, v92
	v_add_f32_e32 v136, v136, v93
	ds_read_b128 v[140:143], v218 offset:16384
	v_mfma_f32_32x32x16_bf16 v[32:47], v[188:191], v[112:115], v[32:47]
	v_exp_f32_e32 v94, v94
	v_exp_f32_e32 v95, v95
	v_add_f32_e32 v133, v133, v94
	v_add_f32_e32 v136, v136, v95
	ds_read_b128 v[144:147], v218 offset:20480
	v_mfma_f32_32x32x16_bf16 v[16:31], v[192:195], v[112:115], v[16:31]
	v_cvt_pk_bf16_f32 v124, v88, v89
	v_cvt_pk_bf16_f32 v125, v90, v91
	ds_read_b128 v[148:151], v218 offset:24576
	v_mfma_f32_32x32x16_bf16 v[0:15], v[196:199], v[112:115], v[0:15]
	v_cvt_pk_bf16_f32 v126, v92, v93
	v_cvt_pk_bf16_f32 v127, v94, v95
	ds_read_b128 v[152:155], v218 offset:28672
	v_max3_f32 v224, v64, v65, v66
	v_max3_f32 v225, v67, v68, v69
	v_max3_f32 v224, v224, v70, v71
	v_mfma_f32_32x32x16_bf16 v[80:95], v[156:159], v[108:111], v[236:251]
	v_max3_f32 v225, v225, v72, v73
	v_mfma_f32_32x32x16_bf16 v[80:95], v[160:163], v[104:107], v[80:95]
	v_max3_f32 v224, v224, v74, v75
	ds_read_b128 v[156:159], v219 offset:16384
	v_mfma_f32_32x32x16_bf16 v[80:95], v[164:167], v[100:103], v[80:95]
	v_max3_f32 v225, v225, v76, v77
	ds_read_b128 v[160:163], v219 offset:20480
	v_mfma_f32_32x32x16_bf16 v[80:95], v[168:171], v[96:99], v[80:95]
	v_max3_f32 v224, v224, v78, v79
	ds_read_b128 v[164:167], v219 offset:24576
	s_waitcnt lgkmcnt(7)
	v_mfma_f32_32x32x16_bf16 v[48:63], v[200:203], v[116:119], v[48:63]
	ds_read_b128 v[168:171], v219 offset:28672
	s_nop 4
	v_mfma_f32_32x32x16_bf16 v[32:47], v[204:207], v[116:119], v[32:47]
	s_nop 1
	v_max3_f32 v224, v224, v80, v81
	v_max3_f32 v225, v225, v82, v83
	v_max3_f32 v224, v224, v84, v85
	v_max3_f32 v225, v225, v86, v87
	v_mfma_f32_32x32x16_bf16 v[16:31], v[208:211], v[116:119], v[16:31]
	v_max3_f32 v224, v224, v88, v89
	v_max3_f32 v225, v225, v90, v91
	v_max3_f32 v224, v224, v92, v93
	v_max3_f32 v225, v225, v94, v95
	v_max_f32_e32 v224, v224, v225
	v_mov_b32_e32 v225, v224
	s_nop 1
	v_permlane32_swap_b32_e32 v224, v225
	v_max_f32_e32 v224, v224, v225
	v_cmp_lt_f32_e32 vcc, 0x41000000, v224
	v_mfma_f32_32x32x16_bf16 v[0:15], v[212:215], v[116:119], v[0:15]
	s_nop 1
	s_cmp_lg_u64 vcc, 0
	s_cbranch_scc1 .Lda_rareA_0b

; #define LAS __attribute__((address_space(3)))
; #define MFMA32(a, b, c) __builtin_amdgcn_mfma_f32_32x32x16_bf16((a), (b), (c), 0, 0, 0)
; __device__ __forceinline__ void att1_load(bf16x8 (&kf)[8], bf16x8 (&vf)[8], const LAS unsigned char* kslot, int ka, const LAS unsigned char* vslot, int va) {
; #pragma unroll
;     for (int ks = 0; ks < 4; ++ks) { const LAS unsigned char* p = kslot + (ka ^ (ks * 32)); kf[2 * ks] = *(const LAS bf16x8*)p; kf[2 * ks + 1] = *(const LAS bf16x8*)(p + 32 * 256); }
; #pragma unroll
;     for (int kk = 0; kk < 2; ++kk)
; #pragma unroll
;         for (int db = 0; db < 4; ++db) vf[kk * 4 + db] = *(const LAS bf16x8*)(vslot + ((va ^ (kk * 32)) + db * 4096));
; }
; __device__ __forceinline__ void att1_load2(bf16x8 (&vg)[8], const LAS unsigned char* vslot, int va) {
; #pragma unroll
;     for (int kk = 2; kk < 4; ++kk)
; #pragma unroll
;         for (int db = 0; db < 4; ++db) vg[(kk - 2) * 4 + db] = *(const LAS bf16x8*)(vslot + ((va ^ (kk * 32)) + db * 4096));
; }
; __device__ __forceinline__ void att1_qk(f32x16& s0, f32x16& s1, const bf16x8 (&kf)[8], const bf16x8 (&qf)[4]) {
;     f32x16 z;
; #pragma unroll
;     for (int i = 0; i < 16; ++i) z[i] = 0.f;
;     s0 = MFMA32(kf[0], qf[0], z); s1 = MFMA32(kf[1], qf[0], z);
; #pragma unroll
;     for (int ks = 1; ks < 4; ++ks) { s0 = MFMA32(kf[2 * ks], qf[ks], s0); s1 = MFMA32(kf[2 * ks + 1], qf[ks], s1); }
; }
; __device__ __forceinline__ void att1_pv(f32x16 (&o)[4], const bf16x8 (&vf)[8], const bf16x8 (&vg)[8], const bf16x8 (&pf)[4]) {
; #pragma unroll
;     for (int kk = 0; kk < 2; ++kk)
; #pragma unroll
;         for (int db = 0; db < 4; ++db) o[db] = MFMA32(vf[kk * 4 + db], pf[kk], o[db]);
; #pragma unroll
;     for (int kk = 2; kk < 4; ++kk)
; #pragma unroll
;         for (int db = 0; db < 4; ++db) o[db] = MFMA32(vg[(kk - 2) * 4 + db], pf[kk], o[db]);
; }
; template <int MODE>
; __device__ __forceinline__ void attn_phase(LAS unsigned char* lds, const bf16* Qp, const bf16* Kp, const bf16* KPEp, const bf16* Vtp, bf16* CAT, float lam, int vcu, int G) {
;     ...
;             ATT1_ITER(pfB, pf, 0, false);
;             for (int i2 = 1; i2 < 127; i2 += 2) {
;                 ATT1_ITER(pf, pfB, i2, true);
;                 ATT1_ITER(pfB, pf, i2 + 1, true);
.Lda_skipB_0b:
	s_waitcnt vmcnt(0) lgkmcnt(0)
	s_barrier
	ds_read_b128 v[140:143], v132 offset:49152
	ds_read_b128 v[144:147], v137 offset:49152
	ds_read_b128 v[148:151], v138 offset:49152
	ds_read_b128 v[152:155], v139 offset:49152
	ds_read_b128 v[156:159], v132 offset:57344
	ds_read_b128 v[160:163], v137 offset:57344
	ds_read_b128 v[164:167], v138 offset:57344
	ds_read_b128 v[168:171], v139 offset:57344
	ds_read_b128 v[184:187], v216 offset:32768
	ds_read_b128 v[188:191], v216 offset:36864
	ds_read_b128 v[192:195], v216 offset:40960
	ds_read_b128 v[196:199], v216 offset:45056
	v_exp_f32_e32 v80, v80
	v_exp_f32_e32 v81, v81
	v_add_f32_e32 v133, v133, v80
	v_add_f32_e32 v136, v136, v81
	v_exp_f32_e32 v82, v82
	v_exp_f32_e32 v83, v83
	v_add_f32_e32 v133, v133, v82
	v_add_f32_e32 v136, v136, v83
	s_waitcnt lgkmcnt(8)
	v_mfma_f32_32x32x16_bf16 v[64:79], v[140:143], v[108:111], v[236:251]
	v_exp_f32_e32 v84, v84
	v_exp_f32_e32 v85, v85
	v_add_f32_e32 v133, v133, v84
	v_add_f32_e32 v136, v136, v85
	ds_read_b128 v[200:203], v217 offset:32768
	v_mfma_f32_32x32x16_bf16 v[64:79], v[144:147], v[104:107], v[64:79]
	v_exp_f32_e32 v86, v86
	v_exp_f32_e32 v87, v87
	v_add_f32_e32 v133, v133, v86
	v_add_f32_e32 v136, v136, v87
	ds_read_b128 v[204:207], v217 offset:36864
	v_mfma_f32_32x32x16_bf16 v[64:79], v[148:151], v[100:103], v[64:79]
	v_exp_f32_e32 v88, v88
	v_exp_f32_e32 v89, v89
	v_add_f32_e32 v133, v133, v88
	v_add_f32_e32 v136, v136, v89
	v_cvt_pk_bf16_f32 v120, v80, v81
	v_cvt_pk_bf16_f32 v121, v82, v83
	ds_read_b128 v[208:211], v217 offset:40960
	v_mfma_f32_32x32x16_bf16 v[64:79], v[152:155], v[96:99], v[64:79]
	v_exp_f32_e32 v90, v90
	v_exp_f32_e32 v91, v91
	v_add_f32_e32 v133, v133, v90
	v_add_f32_e32 v136, v136, v91
	v_cvt_pk_bf16_f32 v122, v84, v85
	v_cvt_pk_bf16_f32 v123, v86, v87
	ds_read_b128 v[212:215], v217 offset:45056
	s_waitcnt lgkmcnt(4)
	v_mfma_f32_32x32x16_bf16 v[48:63], v[184:187], v[112:115], v[48:63]
	v_exp_f32_e32 v92, v92
	v_exp_f32_e32 v93, v93
	v_add_f32_e32 v133, v133, v92
	v_add_f32_e32 v136, v136, v93
	ds_read_b128 v[140:143], v218 offset:32768
	v_mfma_f32_32x32x16_bf16 v[32:47], v[188:191], v[112:115], v[32:47]
	v_exp_f32_e32 v94, v94
	v_exp_f32_e32 v95, v95
	v_add_f32_e32 v133, v133, v94
	v_add_f32_e32 v136, v136, v95
	ds_read_b128 v[144:147], v218 offset:36864
	v_mfma_f32_32x32x16_bf16 v[16:31], v[192:195], v[112:115], v[16:31]
	v_cvt_pk_bf16_f32 v124, v88, v89
	v_cvt_pk_bf16_f32 v125, v90, v91
	ds_read_b128 v[148:151], v218 offset:40960
	v_mfma_f32_32x32x16_bf16 v[0:15], v[196:199], v[112:115], v[0:15]
	v_cvt_pk_bf16_f32 v126, v92, v93
	v_cvt_pk_bf16_f32 v127, v94, v95
	ds_read_b128 v[152:155], v218 offset:45056
	v_max3_f32 v224, v64, v65, v66
	v_max3_f32 v225, v67, v68, v69
	v_max3_f32 v224, v224, v70, v71
	v_mfma_f32_32x32x16_bf16 v[80:95], v[156:159], v[108:111], v[236:251]
	s_add_i32 m0, s58, 0x4000
	v_max3_f32 v225, v225, v72, v73
	global_load_lds_dwordx4 v128, s[8:9]
	s_add_i32 m0, s58, 0x6000
	s_nop 0
	global_load_lds_dwordx4 v129, s[8:9]
	s_add_u32 s8, s8, 0x4000
	s_addc_u32 s9, s9, 0
	v_mfma_f32_32x32x16_bf16 v[80:95], v[160:163], v[104:107], v[80:95]
	s_add_i32 m0, s58, 0x8000
	v_max3_f32 v224, v224, v74, v75
	global_load_lds_dwordx4 v128, s[8:9]
	s_add_i32 m0, s58, 0xa000
	ds_read_b128 v[156:159], v219 offset:32768
	global_load_lds_dwordx4 v129, s[8:9]
	s_add_u32 s8, s8, 0x4000
	s_addc_u32 s9, s9, 0
	v_mfma_f32_32x32x16_bf16 v[80:95], v[164:167], v[100:103], v[80:95]
	s_add_i32 m0, s65, 0x0
	v_max3_f32 v225, v225, v76, v77
	global_load_lds_dwordx4 v130, s[10:11]
	s_add_i32 m0, s65, 0x2000
	ds_read_b128 v[160:163], v219 offset:36864
	global_load_lds_dwordx4 v131, s[10:11]
	s_add_u32 s10, s10, 0x80
	s_addc_u32 s11, s11, 0
	v_mfma_f32_32x32x16_bf16 v[80:95], v[168:171], v[96:99], v[80:95]
	s_add_i32 m0, s65, 0x4000
	v_max3_f32 v224, v224, v78, v79
	global_load_lds_dwordx4 v130, s[10:11]
	s_add_i32 m0, s65, 0x6000
	ds_read_b128 v[164:167], v219 offset:40960
	global_load_lds_dwordx4 v131, s[10:11]
	s_add_u32 s10, s10, 0x80
	s_addc_u32 s11, s11, 0
	s_waitcnt lgkmcnt(7)
	v_mfma_f32_32x32x16_bf16 v[48:63], v[200:203], v[116:119], v[48:63]
	ds_read_b128 v[168:171], v219 offset:45056
	v_mfma_f32_32x32x16_bf16 v[32:47], v[204:207], v[116:119], v[32:47]
	s_nop 1
	v_max3_f32 v224, v224, v80, v81
	v_max3_f32 v225, v225, v82, v83
	v_max3_f32 v224, v224, v84, v85
	v_max3_f32 v225, v225, v86, v87
	v_mfma_f32_32x32x16_bf16 v[16:31], v[208:211], v[116:119], v[16:31]
	v_max3_f32 v224, v224, v88, v89
	v_max3_f32 v225, v225, v90, v91
	v_max3_f32 v224, v224, v92, v93
	v_max3_f32 v225, v225, v94, v95
	v_max_f32_e32 v224, v224, v225
	v_mov_b32_e32 v225, v224
	s_nop 1
	v_permlane32_swap_b32_e32 v224, v225
	v_max_f32_e32 v224, v224, v225
	v_cmp_lt_f32_e32 vcc, 0x41000000, v224
	v_mfma_f32_32x32x16_bf16 v[0:15], v[212:215], v[116:119], v[0:15]
	s_nop 1
	s_cmp_lg_u64 vcc, 0
	s_cbranch_scc1 .Lda_rareA_1a

; #define LAS __attribute__((address_space(3)))
; #define MFMA32(a, b, c) __builtin_amdgcn_mfma_f32_32x32x16_bf16((a), (b), (c), 0, 0, 0)
; __device__ __forceinline__ void att1_load(bf16x8 (&kf)[8], bf16x8 (&vf)[8], const LAS unsigned char* kslot, int ka, const LAS unsigned char* vslot, int va) {
; #pragma unroll
;     for (int ks = 0; ks < 4; ++ks) { const LAS unsigned char* p = kslot + (ka ^ (ks * 32)); kf[2 * ks] = *(const LAS bf16x8*)p; kf[2 * ks + 1] = *(const LAS bf16x8*)(p + 32 * 256); }
; #pragma unroll
;     for (int kk = 0; kk < 2; ++kk)
; #pragma unroll
;         for (int db = 0; db < 4; ++db) vf[kk * 4 + db] = *(const LAS bf16x8*)(vslot + ((va ^ (kk * 32)) + db * 4096));
; }
; __device__ __forceinline__ void att1_load2(bf16x8 (&vg)[8], const LAS unsigned char* vslot, int va) {
; #pragma unroll
;     for (int kk = 2; kk < 4; ++kk)
; #pragma unroll
;         for (int db = 0; db < 4; ++db) vg[(kk - 2) * 4 + db] = *(const LAS bf16x8*)(vslot + ((va ^ (kk * 32)) + db * 4096));
; }
; __device__ __forceinline__ void att1_qk(f32x16& s0, f32x16& s1, const bf16x8 (&kf)[8], const bf16x8 (&qf)[4]) {
;     f32x16 z;
; #pragma unroll
;     for (int i = 0; i < 16; ++i) z[i] = 0.f;
;     s0 = MFMA32(kf[0], qf[0], z); s1 = MFMA32(kf[1], qf[0], z);
; #pragma unroll
;     for (int ks = 1; ks < 4; ++ks) { s0 = MFMA32(kf[2 * ks], qf[ks], s0); s1 = MFMA32(kf[2 * ks + 1], qf[ks], s1); }
; }
; __device__ __forceinline__ void att1_pv(f32x16 (&o)[4], const bf16x8 (&vf)[8], const bf16x8 (&vg)[8], const bf16x8 (&pf)[4]) {
; #pragma unroll
;     for (int kk = 0; kk < 2; ++kk)
; #pragma unroll
;         for (int db = 0; db < 4; ++db) o[db] = MFMA32(vf[kk * 4 + db], pf[kk], o[db]);
; #pragma unroll
;     for (int kk = 2; kk < 4; ++kk)
; #pragma unroll
;         for (int db = 0; db < 4; ++db) o[db] = MFMA32(vg[(kk - 2) * 4 + db], pf[kk], o[db]);
; }
.Lda_skipB_1a:
	ds_read_b128 v[140:143], v132
	ds_read_b128 v[144:147], v137
	ds_read_b128 v[148:151], v138
	ds_read_b128 v[152:155], v139
	ds_read_b128 v[156:159], v132 offset:8192
	ds_read_b128 v[160:163], v137 offset:8192
	ds_read_b128 v[164:167], v138 offset:8192
	ds_read_b128 v[168:171], v139 offset:8192
	ds_read_b128 v[184:187], v216 offset:49152
	ds_read_b128 v[188:191], v216 offset:53248
	ds_read_b128 v[192:195], v216 offset:57344
	ds_read_b128 v[196:199], v216 offset:61440
	v_exp_f32_e32 v80, v80
	v_exp_f32_e32 v81, v81
	v_add_f32_e32 v133, v133, v80
	v_add_f32_e32 v136, v136, v81
	v_exp_f32_e32 v82, v82
	v_exp_f32_e32 v83, v83
	v_add_f32_e32 v133, v133, v82
	v_add_f32_e32 v136, v136, v83
	s_waitcnt lgkmcnt(8)
	v_mfma_f32_32x32x16_bf16 v[64:79], v[140:143], v[108:111], v[236:251]
	v_exp_f32_e32 v84, v84
	v_exp_f32_e32 v85, v85
	v_add_f32_e32 v133, v133, v84
	v_add_f32_e32 v136, v136, v85
	ds_read_b128 v[200:203], v217 offset:49152
	v_mfma_f32_32x32x16_bf16 v[64:79], v[144:147], v[104:107], v[64:79]
	v_exp_f32_e32 v86, v86
	v_exp_f32_e32 v87, v87
	v_add_f32_e32 v133, v133, v86
	v_add_f32_e32 v136, v136, v87
	ds_read_b128 v[204:207], v217 offset:53248
	v_mfma_f32_32x32x16_bf16 v[64:79], v[148:151], v[100:103], v[64:79]
	v_exp_f32_e32 v88, v88
	v_exp_f32_e32 v89, v89
	v_add_f32_e32 v133, v133, v88
	v_add_f32_e32 v136, v136, v89
	v_cvt_pk_bf16_f32 v120, v80, v81
	v_cvt_pk_bf16_f32 v121, v82, v83
	ds_read_b128 v[208:211], v217 offset:57344
	v_mfma_f32_32x32x16_bf16 v[64:79], v[152:155], v[96:99], v[64:79]
	v_exp_f32_e32 v90, v90
	v_exp_f32_e32 v91, v91
	v_add_f32_e32 v133, v133, v90
	v_add_f32_e32 v136, v136, v91
	v_cvt_pk_bf16_f32 v122, v84, v85
	v_cvt_pk_bf16_f32 v123, v86, v87
	ds_read_b128 v[212:215], v217 offset:61440
	s_waitcnt lgkmcnt(4)
	v_mfma_f32_32x32x16_bf16 v[48:63], v[184:187], v[112:115], v[48:63]
	v_exp_f32_e32 v92, v92
	v_exp_f32_e32 v93, v93
	v_add_f32_e32 v133, v133, v92
	v_add_f32_e32 v136, v136, v93
	ds_read_b128 v[140:143], v218 offset:49152
	v_mfma_f32_32x32x16_bf16 v[32:47], v[188:191], v[112:115], v[32:47]
	v_exp_f32_e32 v94, v94
	v_exp_f32_e32 v95, v95
	v_add_f32_e32 v133, v133, v94
	v_add_f32_e32 v136, v136, v95
	ds_read_b128 v[144:147], v218 offset:53248
	v_mfma_f32_32x32x16_bf16 v[16:31], v[192:195], v[112:115], v[16:31]
	v_cvt_pk_bf16_f32 v124, v88, v89
	v_cvt_pk_bf16_f32 v125, v90, v91
	ds_read_b128 v[148:151], v218 offset:57344
	v_mfma_f32_32x32x16_bf16 v[0:15], v[196:199], v[112:115], v[0:15]
	v_cvt_pk_bf16_f32 v126, v92, v93
	v_cvt_pk_bf16_f32 v127, v94, v95
	ds_read_b128 v[152:155], v218 offset:61440
	v_max3_f32 v224, v64, v65, v66
	v_max3_f32 v225, v67, v68, v69
	v_max3_f32 v224, v224, v70, v71
	v_mfma_f32_32x32x16_bf16 v[80:95], v[156:159], v[108:111], v[236:251]
	v_max3_f32 v225, v225, v72, v73
	v_mfma_f32_32x32x16_bf16 v[80:95], v[160:163], v[104:107], v[80:95]
	v_max3_f32 v224, v224, v74, v75
	ds_read_b128 v[156:159], v219 offset:49152
	v_mfma_f32_32x32x16_bf16 v[80:95], v[164:167], v[100:103], v[80:95]
	v_max3_f32 v225, v225, v76, v77
	ds_read_b128 v[160:163], v219 offset:53248
	v_mfma_f32_32x32x16_bf16 v[80:95], v[168:171], v[96:99], v[80:95]
	v_max3_f32 v224, v224, v78, v79
	ds_read_b128 v[164:167], v219 offset:57344
	s_waitcnt lgkmcnt(7)
	v_mfma_f32_32x32x16_bf16 v[48:63], v[200:203], v[116:119], v[48:63]
	ds_read_b128 v[168:171], v219 offset:61440
	s_nop 4
	v_mfma_f32_32x32x16_bf16 v[32:47], v[204:207], v[116:119], v[32:47]
	s_nop 1
	v_max3_f32 v224, v224, v80, v81
	v_max3_f32 v225, v225, v82, v83
	v_max3_f32 v224, v224, v84, v85
	v_max3_f32 v225, v225, v86, v87
	v_mfma_f32_32x32x16_bf16 v[16:31], v[208:211], v[116:119], v[16:31]
	v_max3_f32 v224, v224, v88, v89
	v_max3_f32 v225, v225, v90, v91
	v_max3_f32 v224, v224, v92, v93
	v_max3_f32 v225, v225, v94, v95
	v_max_f32_e32 v224, v224, v225
	v_mov_b32_e32 v225, v224
	s_nop 1
	v_permlane32_swap_b32_e32 v224, v225
	v_max_f32_e32 v224, v224, v225
	v_cmp_lt_f32_e32 vcc, 0x41000000, v224
	v_mfma_f32_32x32x16_bf16 v[0:15], v[212:215], v[116:119], v[0:15]
	s_nop 1
	s_cmp_lg_u64 vcc, 0
	s_cbranch_scc1 .Lda_rareA_1b

; template <int MODE>
; __device__ __forceinline__ void attn_phase(LAS unsigned char* lds, const bf16* Qp, const bf16* Kp, const bf16* KPEp, const bf16* Vtp, bf16* CAT, float lam, int vcu, int G) {
;     ...
;             for (int i2 = 1; i2 < 127; i2 += 2) {
;                 ATT1_ITER(pf, pfB, i2, true);
;                 ATT1_ITER(pfB, pf, i2 + 1, true);
;             }
;             ATT1_ITER(pf, pfB, 127, true);
.Lda_skipB_1b:
	s_add_i32 s66, s66, 1
	s_cmpk_lt_u32 s66, 31
	s_waitcnt vmcnt(0) lgkmcnt(0)
	s_barrier
	s_cbranch_scc1 .Lda_loop
	ds_read_b128 v[140:143], v132 offset:16384
	ds_read_b128 v[144:147], v137 offset:16384
	ds_read_b128 v[148:151], v138 offset:16384
	ds_read_b128 v[152:155], v139 offset:16384
	ds_read_b128 v[156:159], v132 offset:24576
	ds_read_b128 v[160:163], v137 offset:24576
	ds_read_b128 v[164:167], v138 offset:24576
	ds_read_b128 v[168:171], v139 offset:24576
	ds_read_b128 v[184:187], v216
	ds_read_b128 v[188:191], v216 offset:4096
	ds_read_b128 v[192:195], v216 offset:8192
	ds_read_b128 v[196:199], v216 offset:12288
	v_exp_f32_e32 v80, v80
	v_exp_f32_e32 v81, v81
	v_add_f32_e32 v133, v133, v80
	v_add_f32_e32 v136, v136, v81
	v_exp_f32_e32 v82, v82
	v_exp_f32_e32 v83, v83
	v_add_f32_e32 v133, v133, v82
	v_add_f32_e32 v136, v136, v83
	s_waitcnt lgkmcnt(8)
	v_mfma_f32_32x32x16_bf16 v[64:79], v[140:143], v[108:111], v[236:251]
	v_exp_f32_e32 v84, v84
	v_exp_f32_e32 v85, v85
	v_add_f32_e32 v133, v133, v84
	v_add_f32_e32 v136, v136, v85
	ds_read_b128 v[200:203], v217
	v_mfma_f32_32x32x16_bf16 v[64:79], v[144:147], v[104:107], v[64:79]
	v_exp_f32_e32 v86, v86
	v_exp_f32_e32 v87, v87
	v_add_f32_e32 v133, v133, v86
	v_add_f32_e32 v136, v136, v87
	ds_read_b128 v[204:207], v217 offset:4096
	v_mfma_f32_32x32x16_bf16 v[64:79], v[148:151], v[100:103], v[64:79]
	v_exp_f32_e32 v88, v88
	v_exp_f32_e32 v89, v89
	v_add_f32_e32 v133, v133, v88
	v_add_f32_e32 v136, v136, v89
	v_cvt_pk_bf16_f32 v120, v80, v81
	v_cvt_pk_bf16_f32 v121, v82, v83
	ds_read_b128 v[208:211], v217 offset:8192
	v_mfma_f32_32x32x16_bf16 v[64:79], v[152:155], v[96:99], v[64:79]
	v_exp_f32_e32 v90, v90
	v_exp_f32_e32 v91, v91
	v_add_f32_e32 v133, v133, v90
	v_add_f32_e32 v136, v136, v91
	v_cvt_pk_bf16_f32 v122, v84, v85
	v_cvt_pk_bf16_f32 v123, v86, v87
	ds_read_b128 v[212:215], v217 offset:12288
	s_waitcnt lgkmcnt(4)
	v_mfma_f32_32x32x16_bf16 v[48:63], v[184:187], v[112:115], v[48:63]
	v_exp_f32_e32 v92, v92
	v_exp_f32_e32 v93, v93
	v_add_f32_e32 v133, v133, v92
	v_add_f32_e32 v136, v136, v93
	ds_read_b128 v[140:143], v218
	v_mfma_f32_32x32x16_bf16 v[32:47], v[188:191], v[112:115], v[32:47]
	v_exp_f32_e32 v94, v94
	v_exp_f32_e32 v95, v95
	v_add_f32_e32 v133, v133, v94
	v_add_f32_e32 v136, v136, v95
	ds_read_b128 v[144:147], v218 offset:4096
	v_mfma_f32_32x32x16_bf16 v[16:31], v[192:195], v[112:115], v[16:31]
	v_cvt_pk_bf16_f32 v124, v88, v89
	v_cvt_pk_bf16_f32 v125, v90, v91
	ds_read_b128 v[148:151], v218 offset:8192
	v_mfma_f32_32x32x16_bf16 v[0:15], v[196:199], v[112:115], v[0:15]
	v_cvt_pk_bf16_f32 v126, v92, v93
	v_cvt_pk_bf16_f32 v127, v94, v95
	ds_read_b128 v[152:155], v218 offset:12288
	v_max3_f32 v224, v64, v65, v66
	v_max3_f32 v225, v67, v68, v69
	v_max3_f32 v224, v224, v70, v71
	v_mfma_f32_32x32x16_bf16 v[80:95], v[156:159], v[108:111], v[236:251]
	s_add_i32 m0, s58, 0xc000
	v_max3_f32 v225, v225, v72, v73
	global_load_lds_dwordx4 v128, s[8:9]
	s_add_i32 m0, s58, 0xe000
	s_nop 0
	global_load_lds_dwordx4 v129, s[8:9]
	s_add_u32 s8, s8, 0x4000
	s_addc_u32 s9, s9, 0
	v_mfma_f32_32x32x16_bf16 v[80:95], v[160:163], v[104:107], v[80:95]
	s_add_i32 m0, s58, 0x0
	v_max3_f32 v224, v224, v74, v75
	global_load_lds_dwordx4 v128, s[8:9]
	s_add_i32 m0, s58, 0x2000
	ds_read_b128 v[156:159], v219
	global_load_lds_dwordx4 v129, s[8:9]
	s_add_u32 s8, s8, 0x4000
	s_addc_u32 s9, s9, 0
	v_mfma_f32_32x32x16_bf16 v[80:95], v[164:167], v[100:103], v[80:95]
	s_add_i32 m0, s65, 0x8000
	v_max3_f32 v225, v225, v76, v77
	global_load_lds_dwordx4 v130, s[10:11]
	s_add_i32 m0, s65, 0xa000
	ds_read_b128 v[160:163], v219 offset:4096
	global_load_lds_dwordx4 v131, s[10:11]
	s_add_u32 s10, s10, 0x80
	s_addc_u32 s11, s11, 0
	v_mfma_f32_32x32x16_bf16 v[80:95], v[168:171], v[96:99], v[80:95]
	s_add_i32 m0, s65, 0xc000
	v_max3_f32 v224, v224, v78, v79
	global_load_lds_dwordx4 v130, s[10:11]
	s_add_i32 m0, s65, 0xe000
	ds_read_b128 v[164:167], v219 offset:8192
	global_load_lds_dwordx4 v131, s[10:11]
	s_add_u32 s10, s10, 0x80
	s_addc_u32 s11, s11, 0
	s_waitcnt lgkmcnt(7)
	v_mfma_f32_32x32x16_bf16 v[48:63], v[200:203], v[116:119], v[48:63]
	ds_read_b128 v[168:171], v219 offset:12288
	v_mfma_f32_32x32x16_bf16 v[32:47], v[204:207], v[116:119], v[32:47]
	s_nop 1
	v_max3_f32 v224, v224, v80, v81
	v_max3_f32 v225, v225, v82, v83
	v_max3_f32 v224, v224, v84, v85
	v_max3_f32 v225, v225, v86, v87
	v_mfma_f32_32x32x16_bf16 v[16:31], v[208:211], v[116:119], v[16:31]
	v_max3_f32 v224, v224, v88, v89
	v_max3_f32 v225, v225, v90, v91
	v_max3_f32 v224, v224, v92, v93
	v_max3_f32 v225, v225, v94, v95
	v_max_f32_e32 v224, v224, v225
	v_mov_b32_e32 v225, v224
	s_nop 1
	v_permlane32_swap_b32_e32 v224, v225
	v_max_f32_e32 v224, v224, v225
	v_cmp_lt_f32_e32 vcc, 0x41000000, v224
	v_mfma_f32_32x32x16_bf16 v[0:15], v[212:215], v[116:119], v[0:15]
	s_nop 1
	s_cmp_lg_u64 vcc, 0
	s_cbranch_scc1 .Lda_rareA_2a

; template <int MODE>
; __device__ __forceinline__ void attn_phase(LAS unsigned char* lds, const bf16* Qp, const bf16* Kp, const bf16* KPEp, const bf16* Vtp, bf16* CAT, float lam, int vcu, int G) {
;     ...
;             ATT1_ITER(pfB, pf, 0, false);
;             for (int i2 = 1; i2 < 127; i2 += 2) {
;                 ATT1_ITER(pf, pfB, i2, true);
;                 ATT1_ITER(pfB, pf, i2 + 1, true);
;             }
;             ATT1_ITER(pf, pfB, 127, true);
.Lda_skipB_2b:
	s_waitcnt vmcnt(0) lgkmcnt(0)
	s_barrier
	ds_read_b128 v[140:143], v132 offset:49152
	ds_read_b128 v[144:147], v137 offset:49152
	ds_read_b128 v[148:151], v138 offset:49152
	ds_read_b128 v[152:155], v139 offset:49152
	ds_read_b128 v[156:159], v132 offset:57344
	ds_read_b128 v[160:163], v137 offset:57344
	ds_read_b128 v[164:167], v138 offset:57344
	ds_read_b128 v[168:171], v139 offset:57344
	ds_read_b128 v[184:187], v216 offset:32768
	ds_read_b128 v[188:191], v216 offset:36864
	ds_read_b128 v[192:195], v216 offset:40960
	ds_read_b128 v[196:199], v216 offset:45056
	v_exp_f32_e32 v80, v80
	v_exp_f32_e32 v81, v81
	v_add_f32_e32 v133, v133, v80
	v_add_f32_e32 v136, v136, v81
	v_exp_f32_e32 v82, v82
	v_exp_f32_e32 v83, v83
	v_add_f32_e32 v133, v133, v82
	v_add_f32_e32 v136, v136, v83
	s_waitcnt lgkmcnt(8)
	v_mfma_f32_32x32x16_bf16 v[64:79], v[140:143], v[108:111], v[236:251]
	v_exp_f32_e32 v84, v84
	v_exp_f32_e32 v85, v85
	v_add_f32_e32 v133, v133, v84
	v_add_f32_e32 v136, v136, v85
	ds_read_b128 v[200:203], v217 offset:32768
	v_mfma_f32_32x32x16_bf16 v[64:79], v[144:147], v[104:107], v[64:79]
	v_exp_f32_e32 v86, v86
	v_exp_f32_e32 v87, v87
	v_add_f32_e32 v133, v133, v86
	v_add_f32_e32 v136, v136, v87
	ds_read_b128 v[204:207], v217 offset:36864
	v_mfma_f32_32x32x16_bf16 v[64:79], v[148:151], v[100:103], v[64:79]
	v_exp_f32_e32 v88, v88
	v_exp_f32_e32 v89, v89
	v_add_f32_e32 v133, v133, v88
	v_add_f32_e32 v136, v136, v89
	v_cvt_pk_bf16_f32 v120, v80, v81
	v_cvt_pk_bf16_f32 v121, v82, v83
	ds_read_b128 v[208:211], v217 offset:40960
	v_mfma_f32_32x32x16_bf16 v[64:79], v[152:155], v[96:99], v[64:79]
	v_exp_f32_e32 v90, v90
	v_exp_f32_e32 v91, v91
	v_add_f32_e32 v133, v133, v90
	v_add_f32_e32 v136, v136, v91
	v_cvt_pk_bf16_f32 v122, v84, v85
	v_cvt_pk_bf16_f32 v123, v86, v87
	ds_read_b128 v[212:215], v217 offset:45056
	s_waitcnt lgkmcnt(4)
	v_mfma_f32_32x32x16_bf16 v[48:63], v[184:187], v[112:115], v[48:63]
	v_exp_f32_e32 v92, v92
	v_exp_f32_e32 v93, v93
	v_add_f32_e32 v133, v133, v92
	v_add_f32_e32 v136, v136, v93
	ds_read_b128 v[140:143], v218 offset:32768
	v_mfma_f32_32x32x16_bf16 v[32:47], v[188:191], v[112:115], v[32:47]
	v_exp_f32_e32 v94, v94
	v_exp_f32_e32 v95, v95
	v_add_f32_e32 v133, v133, v94
	v_add_f32_e32 v136, v136, v95
	ds_read_b128 v[144:147], v218 offset:36864
	v_mfma_f32_32x32x16_bf16 v[16:31], v[192:195], v[112:115], v[16:31]
	v_cvt_pk_bf16_f32 v124, v88, v89
	v_cvt_pk_bf16_f32 v125, v90, v91
	ds_read_b128 v[148:151], v218 offset:40960
	v_mfma_f32_32x32x16_bf16 v[0:15], v[196:199], v[112:115], v[0:15]
	v_cvt_pk_bf16_f32 v126, v92, v93
	v_cvt_pk_bf16_f32 v127, v94, v95
	ds_read_b128 v[152:155], v218 offset:45056
	v_max3_f32 v224, v64, v65, v66
	v_max3_f32 v225, v67, v68, v69
	v_max3_f32 v224, v224, v70, v71
	v_mfma_f32_32x32x16_bf16 v[80:95], v[156:159], v[108:111], v[236:251]
	v_max3_f32 v225, v225, v72, v73
	v_mfma_f32_32x32x16_bf16 v[80:95], v[160:163], v[104:107], v[80:95]
	v_max3_f32 v224, v224, v74, v75
	ds_read_b128 v[156:159], v219 offset:32768
	v_mfma_f32_32x32x16_bf16 v[80:95], v[164:167], v[100:103], v[80:95]
	v_max3_f32 v225, v225, v76, v77
	ds_read_b128 v[160:163], v219 offset:36864
	v_mfma_f32_32x32x16_bf16 v[80:95], v[168:171], v[96:99], v[80:95]
	v_max3_f32 v224, v224, v78, v79
	ds_read_b128 v[164:167], v219 offset:40960
	s_waitcnt lgkmcnt(7)
	v_mfma_f32_32x32x16_bf16 v[48:63], v[200:203], v[116:119], v[48:63]
	ds_read_b128 v[168:171], v219 offset:45056
	s_nop 4
	v_mfma_f32_32x32x16_bf16 v[32:47], v[204:207], v[116:119], v[32:47]
	s_nop 1
	v_max3_f32 v224, v224, v80, v81
	v_max3_f32 v225, v225, v82, v83
	v_max3_f32 v224, v224, v84, v85
	v_max3_f32 v225, v225, v86, v87
	v_mfma_f32_32x32x16_bf16 v[16:31], v[208:211], v[116:119], v[16:31]
	v_max3_f32 v224, v224, v88, v89
	v_max3_f32 v225, v225, v90, v91
	v_max3_f32 v224, v224, v92, v93
	v_max3_f32 v225, v225, v94, v95
	v_max_f32_e32 v224, v224, v225
	v_mov_b32_e32 v225, v224
	s_nop 1
	v_permlane32_swap_b32_e32 v224, v225
	v_max_f32_e32 v224, v224, v225
	v_cmp_lt_f32_e32 vcc, 0x41000000, v224
	v_mfma_f32_32x32x16_bf16 v[0:15], v[212:215], v[116:119], v[0:15]
	s_nop 1
	s_cmp_lg_u64 vcc, 0
	s_cbranch_scc1 .Lda_rareA_3a

; #define ATT_DMA_K(slotoff) do { _Pragma("unroll") for (int n = 0; n < NKI; ++n) glds16(kp[n], (unsigned)__builtin_amdgcn_readfirstlane(kdma + (slotoff) + n * 8192)); } while (0)
; #define ATT_DMA_V(slotoff) do { _Pragma("unroll") for (int n = 0; n < 2; ++n) glds16(vp[n], (unsigned)__builtin_amdgcn_readfirstlane(vdma + (slotoff) + n * 8192)); } while (0)
; #define ATT_ADV_K() do { _Pragma("unroll") for (int n = 0; n < NKI; ++n) kp[n] += kadv[n]; } while (0)
; #define ATT_ADV_V() do { _Pragma("unroll") for (int n = 0; n < 2; ++n) vp[n] += 64; } while (0)
; #define ATT_RESC_O() do { if (havepend) { _Pragma("unroll") for (int db = 0; db < 4; ++db) _Pragma("unroll") for (int i = 0; i < 16; ++i) o[db][i] *= fpend; havepend = false; } } while (0)
; template <int MODE>
; __device__ __forceinline__ void attn_phase(LAS unsigned char* lds, const bf16* Qp, const bf16* Kp, const bf16* KPEp, const bf16* Vtp, bf16* CAT, float lam, int vcu, int G) {
;     ...
;             ATT1_ITER(pf, pfB, 127, true);
;     ...
; #pragma unroll
;             for (int q = 0; q < 4; ++q) pf[q] = pfB[q];
;         } else {
;         for (int i = 0; i < 128; ++i) {
;             att_qk<MODE>(S0, S1, lds + kr, ka, qf);
;             const float rm = att_rowmax(S0, S1);
;             if (i == 0) mhat = rm;
;             else if (__any(rm - mhat > THR)) { const float dl = fmaxf(rm - mhat, 0.f), f = __builtin_amdgcn_exp2f(-dl); lrun *= f; mhat += dl; fpend = f; havepend = true; }
;             if (i > 0) att_pv(o, vring + vr, va, pf);
;             att_exp(S0, S1, mhat, lrun, pf);
;             ATT_RESC_O();
;             ATT_DMA_K(kw); ATT_DMA_V(vw);
;             if (i + 2 < 127) ATT_ADV_K();
;             if (i + 1 < 127) ATT_ADV_V();
;             kr = (kr == 2 * KB) ? 0 : kr + KB; kw = (kw == 2 * KB) ? 0 : kw + KB;
;             vr = (vr == 2 * VB) ? 0 : vr + VB; vw = (vw == 2 * VB) ? 0 : vw + VB;
;             asm volatile("s_waitcnt vmcnt(5) lgkmcnt(0)\n\ts_barrier" ::: "memory");
;         }
;         }
;         att_pv(o, vring + vr, va, pf);
;         asm volatile("s_waitcnt vmcnt(0) lgkmcnt(0)\n\ts_barrier" ::: "memory");
.Lda_skipB_3a:
	ds_read_b128 v[140:143], v216 offset:49152
	ds_read_b128 v[144:147], v216 offset:53248
	ds_read_b128 v[148:151], v216 offset:57344
	ds_read_b128 v[152:155], v216 offset:61440
	ds_read_b128 v[156:159], v217 offset:49152
	ds_read_b128 v[160:163], v217 offset:53248
	ds_read_b128 v[164:167], v217 offset:57344
	ds_read_b128 v[168:171], v217 offset:61440
	ds_read_b128 v[184:187], v218 offset:49152
	ds_read_b128 v[188:191], v218 offset:53248
	ds_read_b128 v[192:195], v218 offset:57344
	ds_read_b128 v[196:199], v218 offset:61440
	ds_read_b128 v[200:203], v219 offset:49152
	ds_read_b128 v[204:207], v219 offset:53248
	ds_read_b128 v[208:211], v219 offset:57344
	v_exp_f32_e32 v80, v80
	v_exp_f32_e32 v81, v81
	v_add_f32_e32 v133, v133, v80
	v_add_f32_e32 v136, v136, v81
	v_exp_f32_e32 v82, v82
	v_exp_f32_e32 v83, v83
	v_add_f32_e32 v133, v133, v82
	v_add_f32_e32 v136, v136, v83
	v_exp_f32_e32 v84, v84
	v_exp_f32_e32 v85, v85
	v_add_f32_e32 v133, v133, v84
	v_add_f32_e32 v136, v136, v85
	v_exp_f32_e32 v86, v86
	v_exp_f32_e32 v87, v87
	v_add_f32_e32 v133, v133, v86
	v_add_f32_e32 v136, v136, v87
	v_exp_f32_e32 v88, v88
	v_exp_f32_e32 v89, v89
	v_add_f32_e32 v133, v133, v88
	v_add_f32_e32 v136, v136, v89
	v_exp_f32_e32 v90, v90
	v_exp_f32_e32 v91, v91
	v_add_f32_e32 v133, v133, v90
	v_add_f32_e32 v136, v136, v91
	v_exp_f32_e32 v92, v92
	v_exp_f32_e32 v93, v93
	v_add_f32_e32 v133, v133, v92
	v_add_f32_e32 v136, v136, v93
	v_exp_f32_e32 v94, v94
	v_exp_f32_e32 v95, v95
	v_add_f32_e32 v133, v133, v94
	v_add_f32_e32 v136, v136, v95
	v_cvt_pk_bf16_f32 v120, v80, v81
	v_cvt_pk_bf16_f32 v121, v82, v83
	v_cvt_pk_bf16_f32 v122, v84, v85
	v_cvt_pk_bf16_f32 v123, v86, v87
	v_cvt_pk_bf16_f32 v124, v88, v89
	v_cvt_pk_bf16_f32 v125, v90, v91
	v_cvt_pk_bf16_f32 v126, v92, v93
	v_cvt_pk_bf16_f32 v127, v94, v95
	s_nop 1
	s_waitcnt lgkmcnt(14)
	v_mfma_f32_32x32x16_bf16 v[48:63], v[140:143], v[112:115], v[48:63]
	ds_read_b128 v[212:215], v219 offset:61440
	s_waitcnt lgkmcnt(14)
	v_mfma_f32_32x32x16_bf16 v[32:47], v[144:147], v[112:115], v[32:47]
	s_waitcnt lgkmcnt(13)
	v_mfma_f32_32x32x16_bf16 v[16:31], v[148:151], v[112:115], v[16:31]
	s_waitcnt lgkmcnt(12)
	v_mfma_f32_32x32x16_bf16 v[0:15], v[152:155], v[112:115], v[0:15]
	s_waitcnt lgkmcnt(11)
	v_mfma_f32_32x32x16_bf16 v[48:63], v[156:159], v[116:119], v[48:63]
	s_waitcnt lgkmcnt(10)
	v_mfma_f32_32x32x16_bf16 v[32:47], v[160:163], v[116:119], v[32:47]
	s_waitcnt lgkmcnt(9)
	v_mfma_f32_32x32x16_bf16 v[16:31], v[164:167], v[116:119], v[16:31]
	s_waitcnt lgkmcnt(8)
	v_mfma_f32_32x32x16_bf16 v[0:15], v[168:171], v[116:119], v[0:15]
	s_waitcnt lgkmcnt(7)
	v_mfma_f32_32x32x16_bf16 v[48:63], v[184:187], v[120:123], v[48:63]
	s_waitcnt lgkmcnt(6)
	v_mfma_f32_32x32x16_bf16 v[32:47], v[188:191], v[120:123], v[32:47]
	s_waitcnt lgkmcnt(5)
	v_mfma_f32_32x32x16_bf16 v[16:31], v[192:195], v[120:123], v[16:31]
	s_waitcnt lgkmcnt(4)
	v_mfma_f32_32x32x16_bf16 v[0:15], v[196:199], v[120:123], v[0:15]
	s_waitcnt lgkmcnt(3)
	v_mfma_f32_32x32x16_bf16 v[48:63], v[200:203], v[124:127], v[48:63]
	s_waitcnt lgkmcnt(2)
	v_mfma_f32_32x32x16_bf16 v[32:47], v[204:207], v[124:127], v[32:47]
	s_waitcnt lgkmcnt(1)
	v_mfma_f32_32x32x16_bf16 v[16:31], v[208:211], v[124:127], v[16:31]
	s_waitcnt lgkmcnt(0)
	v_mfma_f32_32x32x16_bf16 v[0:15], v[212:215], v[124:127], v[0:15]
	s_waitcnt vmcnt(0) lgkmcnt(0)
	s_barrier
	v_add_f32_e32 v80, v133, v136
	s_mov_b32 m0, s42
	s_lshl_b32 s3, s19, 14
	s_cmp_lg_u32 s18, 1
	s_branch .Lda_epi
